# diff-attention pass: staging registers written to LDS early in the iteration and next-tile loads issued right behind them (full iteration of latency slack)
# speedup vs baseline: 1.0873x; 1.0080x over previous
; __device__ __forceinline__ float bf2f(unsigned short b) { return __uint_as_float((unsigned)b << 16); }
; template <int DV>
; __device__ __forceinline__ void attn_pass(const int tid, unsigned char* smem, const bf16_t* Q0, int qpitch, const bf16_t* Kb, int kpitch, const bf16_t* Vb, int vpitch,
;                                           int b, int ntiles, float kmax, f32x16 (&o)[DV / 32], float& linv) {
;     ...
;     const int lane = tid & 63, wid = __builtin_amdgcn_readfirstlane(tid >> 6), r32 = lane & 31, hi = lane >> 5;
;     bf16x8 qf[4];
;     { const bf16_t* qp = Q0 + (size_t)(wid * 32 + r32) * qpitch + 8 * hi;
; #pragma unroll
;       for (int ds = 0; ds < 4; ++ds) qf[ds] = *(const bf16x8*)(qp + 16 * ds); }
;     float ssq = 0.f;
; #pragma unroll
;     for (int ds = 0; ds < 4; ++ds)
; #pragma unroll
;         for (int j = 0; j < 8; ++j) { const float f = bf2f((unsigned short)qf[ds][j]); ssq += f * f; }
;     ssq = sum_x32(ssq);
;     const float nshift = -sqrtf(ssq) * kmax;
; #pragma unroll
;     for (int d0 = 0; d0 < DV / 32; ++d0)
; #pragma unroll
;         for (int r = 0; r < 16; ++r) o[d0][r] = 0.f;
;     float lsum = 0.f;
;     const int krow = tid >> 3, kch = tid & 7;
;     u32x4 kreg, vreg[NV];
;     auto tile_row = [&](int kt) -> size_t { return kt < 4 ? (size_t)(NLAT + 256 * b + 64 * kt) : (size_t)(SEQ * b + 64 * (kt - 4)); };
;     auto gload = [&](int kt) {
;         const size_t rb = tile_row(kt);
;         kreg = *(const u32x4*)(Kb + (rb + krow) * kpitch + 8 * kch);
; #pragma unroll
;         for (int i = 0; i < NV; ++i) { const int item = tid + 512 * i; const int vr = (DV == 64) ? (item >> 3) : (item >> 4), vc = (DV == 64) ? (item & 7) : (item & 15);
;             vreg[i] = *(const u32x4*)(Vb + (rb + vr) * vpitch + 8 * vc); }
;     };
;     auto lwrite = [&](int buf) {
;         unsigned char* Ks = smem + buf * BUF; unsigned char* Vs = Ks + KBYTES;
;         *(u32x4*)(Ks + krow * KP + 16 * kch) = kreg;
; #pragma unroll
;         for (int i = 0; i < NV; ++i) { const int item = tid + 512 * i; const int vr = (DV == 64) ? (item >> 3) : (item >> 4), vc = (DV == 64) ? (item & 7) : (item & 15);
;             *(u32x4*)(Vs + vr * VP + 16 * vc) = vreg[i]; }
;     };
;     gload(0); lwrite(0); __syncthreads();
.LBB0_405:
	s_xor_b64 s[14:15], s[16:17], -1
	s_lshl_b64 s[0:1], s[0:1], 1
	s_add_u32 s2, s28, s0
	s_addc_u32 s3, s29, s1
	s_add_u32 s16, s30, s0
	v_readfirstlane_b32 s0, v197
	s_addc_u32 s17, s31, s1
	s_ashr_i32 s0, s0, 1
	s_andn2_b32 s0, s0, 31
	v_or_b32_e32 v0, s0, v218
	v_ashrrev_i32_e32 v1, 31, v0
	v_lshlrev_b64 v[0:1], 11, v[0:1]
	v_lshl_add_u64 v[0:1], s[2:3], 0, v[0:1]
	v_lshl_add_u64 v[0:1], v[0:1], 0, v[192:193]
	global_load_dwordx4 v[96:99], v[0:1], off
	global_load_dwordx4 v[100:103], v[0:1], off offset:32
	global_load_dwordx4 v[104:107], v[0:1], off offset:64
	global_load_dwordx4 v[108:111], v[0:1], off offset:96
	s_mov_b32 s0, 0xf800000
	v_mov_b32_e32 v169, v193
	v_lshl_add_u64 v[170:171], s[16:17], 0, v[168:169]
	v_mov_b32_e32 v63, v193
	s_waitcnt vmcnt(3)
	v_and_b32_e32 v1, 0xffff0000, v96
	v_lshlrev_b32_e32 v0, 16, v96
	v_mul_f32_e32 v2, v1, v1
	v_fmac_f32_e32 v2, v0, v0
	v_lshlrev_b32_e32 v0, 16, v97
	v_fmac_f32_e32 v2, v0, v0
	v_and_b32_e32 v0, 0xffff0000, v97
	v_fmac_f32_e32 v2, v0, v0
	v_lshlrev_b32_e32 v0, 16, v98
	v_fmac_f32_e32 v2, v0, v0
	v_and_b32_e32 v0, 0xffff0000, v98
	v_fmac_f32_e32 v2, v0, v0
	v_lshlrev_b32_e32 v0, 16, v99
	v_fmac_f32_e32 v2, v0, v0
	v_and_b32_e32 v0, 0xffff0000, v99
	v_fmac_f32_e32 v2, v0, v0
	s_waitcnt vmcnt(2)
	v_lshlrev_b32_e32 v0, 16, v100
	v_fmac_f32_e32 v2, v0, v0
	v_and_b32_e32 v0, 0xffff0000, v100
	v_fmac_f32_e32 v2, v0, v0
	v_lshlrev_b32_e32 v0, 16, v101
	v_fmac_f32_e32 v2, v0, v0
	v_and_b32_e32 v0, 0xffff0000, v101
	v_fmac_f32_e32 v2, v0, v0
	v_lshlrev_b32_e32 v0, 16, v102
	v_fmac_f32_e32 v2, v0, v0
	v_and_b32_e32 v0, 0xffff0000, v102
	v_fmac_f32_e32 v2, v0, v0
	v_lshlrev_b32_e32 v0, 16, v103
	v_fmac_f32_e32 v2, v0, v0
	v_and_b32_e32 v0, 0xffff0000, v103
	v_fmac_f32_e32 v2, v0, v0
	s_waitcnt vmcnt(1)
	v_lshlrev_b32_e32 v0, 16, v104
	v_fmac_f32_e32 v2, v0, v0
	v_and_b32_e32 v0, 0xffff0000, v104
	v_fmac_f32_e32 v2, v0, v0
	v_lshlrev_b32_e32 v0, 16, v105
	v_fmac_f32_e32 v2, v0, v0
	v_and_b32_e32 v0, 0xffff0000, v105
	v_fmac_f32_e32 v2, v0, v0
	v_lshlrev_b32_e32 v0, 16, v106
	v_fmac_f32_e32 v2, v0, v0
	v_and_b32_e32 v0, 0xffff0000, v106
	v_fmac_f32_e32 v2, v0, v0
	v_lshlrev_b32_e32 v0, 16, v107
	v_fmac_f32_e32 v2, v0, v0
	v_and_b32_e32 v0, 0xffff0000, v107
	v_fmac_f32_e32 v2, v0, v0
	s_waitcnt vmcnt(0)
	v_lshlrev_b32_e32 v0, 16, v108
	v_fmac_f32_e32 v2, v0, v0
	v_and_b32_e32 v0, 0xffff0000, v108
	v_fmac_f32_e32 v2, v0, v0
	v_lshlrev_b32_e32 v0, 16, v109
	v_fmac_f32_e32 v2, v0, v0
	v_and_b32_e32 v0, 0xffff0000, v109
	v_fmac_f32_e32 v2, v0, v0
	v_and_b32_e32 v1, 0xffff0000, v110
	v_lshlrev_b32_e32 v0, 16, v110
	v_pk_mul_f32 v[0:1], v[0:1], v[0:1]
	s_nop 0
	v_add_f32_e32 v0, v0, v2
	v_add_f32_e32 v2, v1, v0
	v_and_b32_e32 v1, 0xffff0000, v111
	v_lshlrev_b32_e32 v0, 16, v111
	v_pk_mul_f32 v[0:1], v[0:1], v[0:1]
	s_nop 0
	v_add_f32_e32 v0, v0, v2
	v_add_f32_e32 v0, v1, v0
	v_mov_b32_e32 v1, v0
	s_nop 1
	v_permlane32_swap_b32_e32 v0, v1
	v_add_f32_e32 v0, v0, v1
	v_cmp_gt_f32_e32 vcc, s0, v0
	v_mul_f32_e32 v1, 0x4f800000, v0
	s_nop 0
	v_cndmask_b32_e32 v0, v0, v1, vcc
	v_sqrt_f32_e32 v1, v0
	s_nop 0
	v_add_u32_e32 v2, -1, v1
	v_fma_f32 v3, -v2, v1, v0
	v_cmp_ge_f32_e64 s[0:1], 0, v3
	v_add_u32_e32 v3, 1, v1
	s_nop 0
	v_cndmask_b32_e64 v2, v1, v2, s[0:1]
	v_fma_f32 v1, -v3, v1, v0
	v_cmp_lt_f32_e64 s[0:1], 0, v1
	s_nop 1
	v_cndmask_b32_e64 v1, v2, v3, s[0:1]
	v_mul_f32_e32 v2, 0x37800000, v1
	v_cndmask_b32_e32 v1, v1, v2, vcc
	v_cmp_class_f32_e32 vcc, v0, v227
	s_nop 1
	v_cndmask_b32_e32 v0, v1, v0, vcc
	v_mul_f32_e64 v32, v214, -v0
	v_mov_b32_e32 v33, v32
	v_mov_b32_e32 v34, v32
	v_mov_b32_e32 v35, v32
	v_mov_b32_e32 v36, v32
	v_mov_b32_e32 v37, v32
	v_mov_b32_e32 v38, v32
	v_mov_b32_e32 v39, v32
	v_mov_b32_e32 v40, v32
	v_mov_b32_e32 v41, v32
	v_mov_b32_e32 v42, v32
	v_mov_b32_e32 v43, v32
	v_mov_b32_e32 v44, v32
	v_mov_b32_e32 v45, v32
	v_mov_b32_e32 v46, v32
	v_mov_b32_e32 v47, v32
	v_mov_b32_e32 v0, 0
	v_mov_b32_e32 v1, 0
	v_mov_b32_e32 v2, 0
	v_mov_b32_e32 v3, 0
	v_mov_b32_e32 v4, 0
	v_mov_b32_e32 v5, 0
	v_mov_b32_e32 v6, 0
	v_mov_b32_e32 v7, 0
	v_mov_b32_e32 v8, 0
	v_mov_b32_e32 v9, 0
	v_mov_b32_e32 v10, 0
	v_mov_b32_e32 v11, 0
	v_mov_b32_e32 v12, 0
	v_mov_b32_e32 v13, 0
	v_mov_b32_e32 v14, 0
	v_mov_b32_e32 v15, 0
	v_mov_b32_e32 v16, 0
	v_mov_b32_e32 v17, 0
	v_mov_b32_e32 v18, 0
	v_mov_b32_e32 v19, 0
	v_mov_b32_e32 v20, 0
	v_mov_b32_e32 v21, 0
	v_mov_b32_e32 v22, 0
	v_mov_b32_e32 v23, 0
	v_mov_b32_e32 v24, 0
	v_mov_b32_e32 v25, 0
	v_mov_b32_e32 v26, 0
	v_mov_b32_e32 v27, 0
	v_mov_b32_e32 v28, 0
	v_mov_b32_e32 v29, 0
	v_mov_b32_e32 v30, 0
	v_mov_b32_e32 v31, 0
	v_mov_b32_e32 v48, 0
	v_mov_b32_e32 v49, 0
	v_mov_b32_e32 v50, 0
	v_mov_b32_e32 v51, 0
	v_mov_b32_e32 v52, 0
	v_mov_b32_e32 v53, 0
	v_mov_b32_e32 v54, 0
	v_mov_b32_e32 v55, 0
	v_mov_b32_e32 v56, 0
	v_mov_b32_e32 v57, 0
	v_mov_b32_e32 v58, 0
	v_mov_b32_e32 v59, 0
	v_mov_b32_e32 v60, 0
	v_mov_b32_e32 v61, 0
	v_mov_b32_e32 v62, 0
	v_mov_b32_e32 v63, 0
	v_mov_b32_e32 v64, 0
	v_mov_b32_e32 v65, 0
	v_mov_b32_e32 v66, 0
	v_mov_b32_e32 v67, 0
	v_mov_b32_e32 v68, 0
	v_mov_b32_e32 v69, 0
	v_mov_b32_e32 v70, 0
	v_mov_b32_e32 v71, 0
	v_mov_b32_e32 v72, 0
	v_mov_b32_e32 v73, 0
	v_mov_b32_e32 v74, 0
	v_mov_b32_e32 v75, 0
	v_mov_b32_e32 v76, 0
	v_mov_b32_e32 v77, 0
	v_mov_b32_e32 v78, 0
	v_mov_b32_e32 v79, 0
	v_mov_b32_e32 v169, 0
	v_readlane_b32 s68, v251, 29
	v_readlane_b32 s69, v251, 30
	s_lshl_b32 s2, s26, 8
	s_add_u32 s68, s68, s2
	s_addc_u32 s69, s69, 0
	s_mov_b64 s[66:67], s[16:17]
	s_lshl_b32 s2, s10, 8
	s_add_i32 s65, s2, 0x8000
	s_lshl_b32 s2, s10, 13
	s_add_i32 s32, s2, 0xffffff00
	v_lshl_add_u32 v166, v136, 10, v168
	v_lshl_add_u32 v167, v134, 10, v140
	v_lshl_add_u32 v132, v144, 10, v140
	s_mov_b32 s70, 0
	s_cmp_lt_u32 s70, 4
	s_cselect_b32 s2, s65, s32
	s_lshl_b32 s3, s70, 6
	s_add_i32 s2, s2, s3
	s_lshl_b32 s2, s2, 10
	s_add_u32 s60, s66, s2
	s_addc_u32 s61, s67, 0
	s_cmp_lt_u32 s70, 4
	s_cselect_b32 s2, s65, s32
	s_lshl_b32 s3, s70, 6
	s_add_i32 s2, s2, s3
	s_lshl_b32 s2, s2, 10
	s_add_u32 s62, s68, s2
	s_addc_u32 s63, s69, 0
	global_load_dwordx4 v[234:237], v166, s[60:61]
	global_load_dwordx4 v[128:131], v167, s[62:63]
	global_load_dwordx4 v[170:173], v132, s[62:63]
	s_mov_b32 s70, 1
	s_cmp_lt_u32 s70, 4
	s_cselect_b32 s2, s65, s32
	s_lshl_b32 s3, s70, 6
	s_add_i32 s2, s2, s3
	s_lshl_b32 s2, s2, 10
	s_add_u32 s60, s66, s2
	s_addc_u32 s61, s67, 0
	global_load_dwordx4 v[198:201], v166, s[60:61]
	v_add_u32_e32 v248, v212, v139
	v_add_u32_e32 v249, v219, v140
	v_add_u32_e32 v133, v220, v140
	s_waitcnt vmcnt(0)
	ds_write_b128 v248, v[234:237]
	ds_write_b128 v248, v[198:201] offset:29696
	ds_write_b128 v249, v[128:131] offset:38912
	ds_write_b128 v133, v[170:173] offset:38912
	s_waitcnt lgkmcnt(0)
	s_barrier
; __device__ __forceinline__ unsigned cvt_pk_bf16(float lo, float hi) { f32x2 v = {lo, hi}; bf16x2_t b = __builtin_convertvector(v, bf16x2_t); return __builtin_bit_cast(unsigned, b); }
; template <int DV>
; __device__ __forceinline__ void attn_pass(const int tid, unsigned char* smem, const bf16_t* Q0, int qpitch, const bf16_t* Kb, int kpitch, const bf16_t* Vb, int vpitch,
;                                           int b, int ntiles, float kmax, f32x16 (&o)[DV / 32], float& linv) {
;     ...
;     gload(0); lwrite(0); __syncthreads();
;     const int nhalf = (lane >> 4) & 1, q4 = (lane & 15) >> 2, p4 = lane & 3;
;     for (int kt = 0; kt < ntiles; ++kt) {
;         if (kt + 1 < ntiles) gload(kt + 1);
;         const unsigned char* Ks = smem + (kt & 1) * BUF; const unsigned char* Vs = Ks + KBYTES;
;         const unsigned char* kp = Ks + r32 * KP + hi * 16;
;         bf16x8 pf[2][2];
; #pragma unroll
;         for (int kb = 0; kb < 2; ++kb) {
;             f32x16 s;
; #pragma unroll
;             for (int r = 0; r < 16; ++r) s[r] = nshift;
; #pragma unroll
;             for (int ds = 0; ds < 4; ++ds) {
;                 const bf16x8 kf = *(const bf16x8*)(kp + kb * 32 * KP + ds * 32);
;                 s = __builtin_amdgcn_mfma_f32_32x32x16_bf16(kf, qf[ds], s, 0, 0, 0);
;             }
;             float ls = 0.f;
; #pragma unroll
;             for (int r = 0; r < 16; ++r) { s[r] = __builtin_amdgcn_exp2f(s[r]); ls += s[r]; }
;             lsum += ls;
; #pragma unroll
;             for (int j = 0; j < 2; ++j) {
;                 u32x4 w0;
;                 w0.x = cvt_pk_bf16(s[8 * j + 0], s[8 * j + 1]); w0.y = cvt_pk_bf16(s[8 * j + 2], s[8 * j + 3]); w0.z = cvt_pk_bf16(s[8 * j + 4], s[8 * j + 5]); w0.w = cvt_pk_bf16(s[8 * j + 6], s[8 * j + 7]);
;                 pf[kb][j] = __builtin_bit_cast(bf16x8, w0);
;             }
;         }
	s_mov_b32 s56, 0
	s_movk_i32 s57, 0x7400
	s_mov_b32 s58, 0xe800
	s_mov_b32 s59, 0
	s_add_i32 s71, s25, -1
	s_add_i32 s70, s59, 2
	s_min_u32 s70, s70, s71
	s_cmp_lt_u32 s70, 4
	s_cselect_b32 s2, s65, s32
	s_lshl_b32 s3, s70, 6
	s_add_i32 s2, s2, s3
	s_lshl_b32 s2, s2, 10
	s_add_u32 s60, s66, s2
	s_addc_u32 s61, s67, 0
	s_add_i32 s70, s59, 1
	s_min_u32 s70, s70, s71
	s_cmp_lt_u32 s70, 4
	s_cselect_b32 s2, s65, s32
	s_lshl_b32 s3, s70, 6
	s_add_i32 s2, s2, s3
	s_lshl_b32 s2, s2, 10
	s_add_u32 s62, s68, s2
	s_addc_u32 s63, s69, 0
	global_load_dwordx4 v[234:237], v166, s[60:61]
	global_load_dwordx4 v[128:131], v167, s[62:63]
	global_load_dwordx4 v[170:173], v132, s[62:63]
	v_add_u32_e32 v174, v213, v138
	ds_read_b128 v[198:201], v174 offset:0
	ds_read_b128 v[202:205], v174 offset:32
	ds_read_b128 v[206:209], v174 offset:64
	ds_read_b128 v[150:153], v174 offset:96
	v_add3_u32 v174, s56, v213, v138
	v_add3_u32 v175, s56, v141, v221
	v_add3_u32 v210, s57, v213, v138
	v_add3_u32 v211, s57, v141, v221
	s_waitcnt lgkmcnt(3)
	v_mfma_f32_32x32x16_bf16 v[80:95], v[198:201], v[96:99], v[32:47]
	ds_read_b128 v[198:201], v174 offset:4608
	v_add3_u32 v248, s58, v212, v139
	v_add3_u32 v249, s58, v219, v140
	v_add3_u32 v133, s58, v220, v140
	s_waitcnt vmcnt(0)
	ds_write_b128 v248, v[234:237]
	ds_write_b128 v249, v[128:131] offset:9216
	ds_write_b128 v133, v[170:173] offset:9216
	s_waitcnt lgkmcnt(6)
	v_mfma_f32_32x32x16_bf16 v[80:95], v[202:205], v[100:103], v[80:95]
	ds_read_b128 v[202:205], v174 offset:4640
	s_add_i32 s71, s25, -1
	s_add_i32 s70, s59, 3
	s_min_u32 s70, s70, s71
	s_cmp_lt_u32 s70, 4
	s_cselect_b32 s2, s65, s32
	s_lshl_b32 s3, s70, 6
	s_add_i32 s2, s2, s3
	s_lshl_b32 s2, s2, 10
	s_add_u32 s60, s66, s2
	s_addc_u32 s61, s67, 0
	s_add_i32 s70, s59, 2
	s_min_u32 s70, s70, s71
	s_cmp_lt_u32 s70, 4
	s_cselect_b32 s2, s65, s32
	s_lshl_b32 s3, s70, 6
	s_add_i32 s2, s2, s3
	s_lshl_b32 s2, s2, 10
	s_add_u32 s62, s68, s2
	s_addc_u32 s63, s69, 0
	s_waitcnt lgkmcnt(6)
	v_mfma_f32_32x32x16_bf16 v[80:95], v[206:209], v[104:107], v[80:95]
	ds_read_b128 v[206:209], v174 offset:4672
	global_load_dwordx4 v[234:237], v166, s[60:61]
	global_load_dwordx4 v[128:131], v167, s[62:63]
	global_load_dwordx4 v[170:173], v132, s[62:63]
	s_waitcnt lgkmcnt(6)
	v_mfma_f32_32x32x16_bf16 v[80:95], v[150:153], v[108:111], v[80:95]
	ds_read_b128 v[150:153], v174 offset:4704
	s_nop 7
	s_waitcnt lgkmcnt(6)
	v_mfma_f32_32x32x16_bf16 v[112:127], v[198:201], v[96:99], v[32:47]
	ds_read_b128 v[198:201], v210 offset:0
	ds_read_b64_tr_b16 v[154:155], v211 offset:9216
	ds_read_b64_tr_b16 v[156:157], v211 offset:11776
	v_exp_f32_e32 v80, v80
	v_exp_f32_e32 v81, v81
	v_exp_f32_e32 v82, v82
	v_add_f32_e32 v169, v169, v80
	v_exp_f32_e32 v83, v83
	v_add_f32_e32 v169, v169, v81
	v_cvt_pk_bf16_f32 v176, v80, v81
	v_exp_f32_e32 v84, v84
	v_add_f32_e32 v169, v169, v82
	v_exp_f32_e32 v85, v85
	v_add_f32_e32 v169, v169, v83
	v_cvt_pk_bf16_f32 v177, v82, v83
	v_exp_f32_e32 v86, v86
	s_waitcnt lgkmcnt(5)
	v_mfma_f32_32x32x16_bf16 v[112:127], v[202:205], v[100:103], v[112:127]
	ds_read_b128 v[202:205], v210 offset:32
	ds_read_b64_tr_b16 v[158:159], v211 offset:9280
	ds_read_b64_tr_b16 v[160:161], v211 offset:11840
	v_add_f32_e32 v169, v169, v84
	v_exp_f32_e32 v87, v87
	v_add_f32_e32 v169, v169, v85
	v_cvt_pk_bf16_f32 v178, v84, v85
	v_exp_f32_e32 v88, v88
	v_add_f32_e32 v169, v169, v86
	v_exp_f32_e32 v89, v89
	v_add_f32_e32 v169, v169, v87
	v_cvt_pk_bf16_f32 v179, v86, v87
	v_exp_f32_e32 v90, v90
	v_add_f32_e32 v169, v169, v88
	v_exp_f32_e32 v91, v91
	v_add_f32_e32 v169, v169, v89
	s_waitcnt lgkmcnt(7)
	v_mfma_f32_32x32x16_bf16 v[112:127], v[206:209], v[104:107], v[112:127]
	ds_read_b128 v[206:209], v210 offset:64
	ds_read_b64_tr_b16 v[162:163], v211 offset:9344
	ds_read_b64_tr_b16 v[164:165], v211 offset:11904
	v_cvt_pk_bf16_f32 v180, v88, v89
	v_exp_f32_e32 v92, v92
	v_add_f32_e32 v169, v169, v90
	v_exp_f32_e32 v93, v93
	v_add_f32_e32 v169, v169, v91
	v_cvt_pk_bf16_f32 v181, v90, v91
	v_exp_f32_e32 v94, v94
	v_add_f32_e32 v169, v169, v92
	v_exp_f32_e32 v95, v95
	v_add_f32_e32 v169, v169, v93
	v_cvt_pk_bf16_f32 v182, v92, v93
	v_add_f32_e32 v169, v169, v94
	v_add_f32_e32 v169, v169, v95
	v_cvt_pk_bf16_f32 v183, v94, v95
	s_waitcnt lgkmcnt(9)
	v_mfma_f32_32x32x16_bf16 v[112:127], v[150:153], v[108:111], v[112:127]
	ds_read_b128 v[150:153], v210 offset:96
	ds_read_b64_tr_b16 v[230:231], v211 offset:9408
	ds_read_b64_tr_b16 v[232:233], v211 offset:11968
	v_add3_u32 v142, s57, v213, v138
	v_add3_u32 v143, s57, v141, v221
	v_add3_u32 v146, s58, v213, v138
	v_add3_u32 v147, s58, v141, v221
	s_mov_b32 s2, s56
	s_mov_b32 s56, s57
	s_mov_b32 s57, s58
	s_mov_b32 s58, s2
	s_add_i32 s59, s59, 1
	v_add3_u32 v248, s58, v212, v139
	v_add3_u32 v249, s58, v219, v140
	v_add3_u32 v133, s58, v220, v140
	s_waitcnt lgkmcnt(0)
	s_barrier
; template <int DV>
; __device__ __forceinline__ void attn_pass(const int tid, unsigned char* smem, const bf16_t* Q0, int qpitch, const bf16_t* Kb, int kpitch, const bf16_t* Vb, int vpitch,
;                                           int b, int ntiles, float kmax, f32x16 (&o)[DV / 32], float& linv) {
;     ...
;     for (int kt = 0; kt < ntiles; ++kt) {
;         if (kt + 1 < ntiles) gload(kt + 1);
;         const unsigned char* Ks = smem + (kt & 1) * BUF; const unsigned char* Vs = Ks + KBYTES;
;         const unsigned char* kp = Ks + r32 * KP + hi * 16;
;         bf16x8 pf[2][2];
; #pragma unroll
;         for (int kb = 0; kb < 2; ++kb) {
;             f32x16 s;
; #pragma unroll
;             for (int r = 0; r < 16; ++r) s[r] = nshift;
; #pragma unroll
;             for (int ds = 0; ds < 4; ++ds) {
;                 const bf16x8 kf = *(const bf16x8*)(kp + kb * 32 * KP + ds * 32);
;                 s = __builtin_amdgcn_mfma_f32_32x32x16_bf16(kf, qf[ds], s, 0, 0, 0);
;             }
;             float ls = 0.f;
; #pragma unroll
;             for (int r = 0; r < 16; ++r) { s[r] = __builtin_amdgcn_exp2f(s[r]); ls += s[r]; }
;             lsum += ls;
; #pragma unroll
;             for (int j = 0; j < 2; ++j) {
;                 u32x4 w0;
;                 w0.x = cvt_pk_bf16(s[8 * j + 0], s[8 * j + 1]); w0.y = cvt_pk_bf16(s[8 * j + 2], s[8 * j + 3]); w0.z = cvt_pk_bf16(s[8 * j + 4], s[8 * j + 5]); w0.w = cvt_pk_bf16(s[8 * j + 6], s[8 * j + 7]);
;                 pf[kb][j] = __builtin_bit_cast(bf16x8, w0);
;             }
;         }
;         const unsigned char* vp = Vs + (4 * hi + q4) * VP + (16 * nhalf + 4 * p4) * 2;
; #pragma unroll
;         for (int d0 = 0; d0 < DV / 32; ++d0) {
; #pragma unroll
;             for (int kb = 0; kb < 2; ++kb)
; #pragma unroll
;                 for (int j = 0; j < 2; ++j) {
;                     const unsigned char* a = vp + (32 * kb + 16 * j) * VP + d0 * 64;
;                     const s16x4 lo = ld_tr(a), h4 = ld_tr(a + 8 * VP);
;                     const bf16x8 vf = (bf16x8){lo[0], lo[1], lo[2], lo[3], h4[0], h4[1], h4[2], h4[3]};
;                     o[d0] = __builtin_amdgcn_mfma_f32_32x32x16_bf16(vf, pf[kb][j], o[d0], 0, 0, 0);
;                 }
;             if (d0 & 1) __builtin_amdgcn_sched_barrier(0);
;         }
;         if (kt + 1 < ntiles) lwrite((kt + 1) & 1);
;         __syncthreads();
.Lcattn_loop:
	v_mfma_f32_32x32x16_bf16 v[80:95], v[198:201], v[96:99], v[32:47]
	ds_read_b128 v[198:201], v142 offset:4608
	v_exp_f32_e32 v112, v112
	v_exp_f32_e32 v113, v113
	v_exp_f32_e32 v114, v114
	v_mfma_f32_32x32x16_bf16 v[80:95], v[202:205], v[100:103], v[80:95]
	ds_read_b128 v[202:205], v142 offset:4640
	v_add_f32_e32 v169, v169, v112
	v_exp_f32_e32 v115, v115
	v_add_f32_e32 v169, v169, v113
	v_cvt_pk_bf16_f32 v184, v112, v113
	v_mfma_f32_32x32x16_bf16 v[80:95], v[206:209], v[104:107], v[80:95]
	ds_read_b128 v[206:209], v142 offset:4672
	v_exp_f32_e32 v116, v116
	v_add_f32_e32 v169, v169, v114
	v_exp_f32_e32 v117, v117
	v_mfma_f32_32x32x16_bf16 v[80:95], v[150:153], v[108:111], v[80:95]
	ds_read_b128 v[150:153], v142 offset:4704
	v_add_f32_e32 v169, v169, v115
	v_cvt_pk_bf16_f32 v185, v114, v115
	v_exp_f32_e32 v118, v118
	v_add_f32_e32 v169, v169, v116
	s_waitcnt lgkmcnt(10)
	v_mfma_f32_32x32x16_bf16 v[0:15], v[154:157], v[176:179], v[0:15]
	ds_read_b64_tr_b16 v[154:155], v143 offset:14336
	ds_read_b64_tr_b16 v[156:157], v143 offset:16896
	s_waitcnt vmcnt(0)
	ds_write_b128 v248, v[234:237]
	v_exp_f32_e32 v119, v119
	v_add_f32_e32 v169, v169, v117
	v_cvt_pk_bf16_f32 v186, v116, v117
	v_exp_f32_e32 v120, v120
	s_waitcnt lgkmcnt(11)
	v_mfma_f32_32x32x16_bf16 v[16:31], v[158:161], v[176:179], v[16:31]
	ds_read_b64_tr_b16 v[158:159], v143 offset:14400
	ds_read_b64_tr_b16 v[160:161], v143 offset:16960
	ds_write_b128 v249, v[128:131] offset:9216
	v_add_f32_e32 v169, v169, v118
	v_exp_f32_e32 v121, v121
	v_add_f32_e32 v169, v169, v119
	s_waitcnt lgkmcnt(12)
	v_mfma_f32_32x32x16_bf16 v[48:63], v[162:165], v[176:179], v[48:63]
	ds_read_b64_tr_b16 v[162:163], v143 offset:14464
	ds_read_b64_tr_b16 v[164:165], v143 offset:17024
	ds_write_b128 v133, v[170:173] offset:9216
	v_cvt_pk_bf16_f32 v187, v118, v119
	v_exp_f32_e32 v122, v122
	v_add_f32_e32 v169, v169, v120
	v_exp_f32_e32 v123, v123
	s_waitcnt lgkmcnt(13)
	v_mfma_f32_32x32x16_bf16 v[64:79], v[230:233], v[176:179], v[64:79]
	ds_read_b64_tr_b16 v[230:231], v143 offset:14528
	ds_read_b64_tr_b16 v[232:233], v143 offset:17088
	s_add_i32 s71, s25, -1
	s_add_i32 s70, s59, 3
	s_min_u32 s70, s70, s71
	s_cmp_lt_u32 s70, 4
	s_cselect_b32 s2, s65, s32
	s_lshl_b32 s3, s70, 6
	s_add_i32 s2, s2, s3
	s_lshl_b32 s2, s2, 10
	s_add_u32 s60, s66, s2
	s_addc_u32 s61, s67, 0
	s_add_i32 s70, s59, 2
	s_min_u32 s70, s70, s71
	s_cmp_lt_u32 s70, 4
	s_cselect_b32 s2, s65, s32
	s_lshl_b32 s3, s70, 6
	s_add_i32 s2, s2, s3
	s_lshl_b32 s2, s2, 10
	s_add_u32 s62, s68, s2
	s_addc_u32 s63, s69, 0
	v_add_f32_e32 v169, v169, v121
	v_cvt_pk_bf16_f32 v188, v120, v121
	v_exp_f32_e32 v124, v124
	s_waitcnt lgkmcnt(9)
	v_mfma_f32_32x32x16_bf16 v[0:15], v[154:157], v[180:183], v[0:15]
	ds_read_b64_tr_b16 v[154:155], v143 offset:19456
	ds_read_b64_tr_b16 v[156:157], v143 offset:22016
	global_load_dwordx4 v[234:237], v166, s[60:61]
	global_load_dwordx4 v[128:131], v167, s[62:63]
	global_load_dwordx4 v[170:173], v132, s[62:63]
	v_add_f32_e32 v169, v169, v122
	v_exp_f32_e32 v125, v125
	v_add_f32_e32 v169, v169, v123
	v_cvt_pk_bf16_f32 v189, v122, v123
	s_waitcnt lgkmcnt(8)
	v_mfma_f32_32x32x16_bf16 v[16:31], v[158:161], v[180:183], v[16:31]
	ds_read_b64_tr_b16 v[158:159], v143 offset:19520
	ds_read_b64_tr_b16 v[160:161], v143 offset:22080
	v_exp_f32_e32 v126, v126
	v_add_f32_e32 v169, v169, v124
	v_exp_f32_e32 v127, v127
	s_waitcnt lgkmcnt(7)
	v_mfma_f32_32x32x16_bf16 v[48:63], v[162:165], v[180:183], v[48:63]
	ds_read_b64_tr_b16 v[162:163], v143 offset:19584
	ds_read_b64_tr_b16 v[164:165], v143 offset:22144
	v_add_f32_e32 v169, v169, v125
	v_cvt_pk_bf16_f32 v190, v124, v125
	v_add_f32_e32 v169, v169, v126
	v_add_f32_e32 v169, v169, v127
	v_cvt_pk_bf16_f32 v191, v126, v127
	s_waitcnt lgkmcnt(6)
	v_mfma_f32_32x32x16_bf16 v[64:79], v[230:233], v[180:183], v[64:79]
	ds_read_b64_tr_b16 v[230:231], v143 offset:19648
	ds_read_b64_tr_b16 v[232:233], v143 offset:22208
	v_mfma_f32_32x32x16_bf16 v[112:127], v[198:201], v[96:99], v[32:47]
	ds_read_b128 v[198:201], v146 offset:0
	v_exp_f32_e32 v80, v80
	v_exp_f32_e32 v81, v81
	v_exp_f32_e32 v82, v82
	v_mfma_f32_32x32x16_bf16 v[112:127], v[202:205], v[100:103], v[112:127]
	ds_read_b128 v[202:205], v146 offset:32
	v_add_f32_e32 v169, v169, v80
	v_exp_f32_e32 v83, v83
	v_add_f32_e32 v169, v169, v81
	v_cvt_pk_bf16_f32 v176, v80, v81
	v_mfma_f32_32x32x16_bf16 v[112:127], v[206:209], v[104:107], v[112:127]
	ds_read_b128 v[206:209], v146 offset:64
	v_exp_f32_e32 v84, v84
	v_add_f32_e32 v169, v169, v82
	v_exp_f32_e32 v85, v85
	v_mfma_f32_32x32x16_bf16 v[112:127], v[150:153], v[108:111], v[112:127]
	ds_read_b128 v[150:153], v146 offset:96
	v_add_f32_e32 v169, v169, v83
	v_cvt_pk_bf16_f32 v177, v82, v83
	v_exp_f32_e32 v86, v86
	v_add_f32_e32 v169, v169, v84
	s_waitcnt lgkmcnt(10)
	v_mfma_f32_32x32x16_bf16 v[0:15], v[154:157], v[184:187], v[0:15]
	ds_read_b64_tr_b16 v[154:155], v143 offset:24576
	ds_read_b64_tr_b16 v[156:157], v143 offset:27136
	v_exp_f32_e32 v87, v87
	v_add_f32_e32 v169, v169, v85
	v_cvt_pk_bf16_f32 v178, v84, v85
	v_exp_f32_e32 v88, v88
	s_waitcnt lgkmcnt(10)
	v_mfma_f32_32x32x16_bf16 v[16:31], v[158:161], v[184:187], v[16:31]
	ds_read_b64_tr_b16 v[158:159], v143 offset:24640
	ds_read_b64_tr_b16 v[160:161], v143 offset:27200
	v_add_f32_e32 v169, v169, v86
	v_exp_f32_e32 v89, v89
	v_add_f32_e32 v169, v169, v87
	s_waitcnt lgkmcnt(10)
	v_mfma_f32_32x32x16_bf16 v[48:63], v[162:165], v[184:187], v[48:63]
	ds_read_b64_tr_b16 v[162:163], v143 offset:24704
	ds_read_b64_tr_b16 v[164:165], v143 offset:27264
	v_cvt_pk_bf16_f32 v179, v86, v87
	v_exp_f32_e32 v90, v90
	v_add_f32_e32 v169, v169, v88
	v_exp_f32_e32 v91, v91
	s_waitcnt lgkmcnt(10)
; template <int DV>
; __device__ __forceinline__ void attn_pass(const int tid, unsigned char* smem, const bf16_t* Q0, int qpitch, const bf16_t* Kb, int kpitch, const bf16_t* Vb, int vpitch,
;                                           int b, int ntiles, float kmax, f32x16 (&o)[DV / 32], float& linv) {
;     ...
;     for (int kt = 0; kt < ntiles; ++kt) {
;         if (kt + 1 < ntiles) gload(kt + 1);
;         const unsigned char* Ks = smem + (kt & 1) * BUF; const unsigned char* Vs = Ks + KBYTES;
;         const unsigned char* kp = Ks + r32 * KP + hi * 16;
;         bf16x8 pf[2][2];
; #pragma unroll
;         for (int kb = 0; kb < 2; ++kb) {
;             f32x16 s;
; #pragma unroll
;             for (int r = 0; r < 16; ++r) s[r] = nshift;
; #pragma unroll
;             for (int ds = 0; ds < 4; ++ds) {
;                 const bf16x8 kf = *(const bf16x8*)(kp + kb * 32 * KP + ds * 32);
;                 s = __builtin_amdgcn_mfma_f32_32x32x16_bf16(kf, qf[ds], s, 0, 0, 0);
;             }
;             float ls = 0.f;
; #pragma unroll
;             for (int r = 0; r < 16; ++r) { s[r] = __builtin_amdgcn_exp2f(s[r]); ls += s[r]; }
;             lsum += ls;
; #pragma unroll
;             for (int j = 0; j < 2; ++j) {
;                 u32x4 w0;
;                 w0.x = cvt_pk_bf16(s[8 * j + 0], s[8 * j + 1]); w0.y = cvt_pk_bf16(s[8 * j + 2], s[8 * j + 3]); w0.z = cvt_pk_bf16(s[8 * j + 4], s[8 * j + 5]); w0.w = cvt_pk_bf16(s[8 * j + 6], s[8 * j + 7]);
;                 pf[kb][j] = __builtin_bit_cast(bf16x8, w0);
;             }
;         }
;         const unsigned char* vp = Vs + (4 * hi + q4) * VP + (16 * nhalf + 4 * p4) * 2;
; #pragma unroll
;         for (int d0 = 0; d0 < DV / 32; ++d0) {
; #pragma unroll
;             for (int kb = 0; kb < 2; ++kb)
; #pragma unroll
;                 for (int j = 0; j < 2; ++j) {
;                     const unsigned char* a = vp + (32 * kb + 16 * j) * VP + d0 * 64;
;                     const s16x4 lo = ld_tr(a), h4 = ld_tr(a + 8 * VP);
;                     const bf16x8 vf = (bf16x8){lo[0], lo[1], lo[2], lo[3], h4[0], h4[1], h4[2], h4[3]};
;                     o[d0] = __builtin_amdgcn_mfma_f32_32x32x16_bf16(vf, pf[kb][j], o[d0], 0, 0, 0);
;                 }
;             if (d0 & 1) __builtin_amdgcn_sched_barrier(0);
;         }
;         if (kt + 1 < ntiles) lwrite((kt + 1) & 1);
;         __syncthreads();
	v_mfma_f32_32x32x16_bf16 v[64:79], v[230:233], v[184:187], v[64:79]
	ds_read_b64_tr_b16 v[230:231], v143 offset:24768
	ds_read_b64_tr_b16 v[232:233], v143 offset:27328
	v_add_f32_e32 v169, v169, v89
	v_cvt_pk_bf16_f32 v180, v88, v89
	v_exp_f32_e32 v92, v92
	s_waitcnt lgkmcnt(6)
	v_mfma_f32_32x32x16_bf16 v[0:15], v[154:157], v[188:191], v[0:15]
	ds_read_b64_tr_b16 v[154:155], v147 offset:9216
	ds_read_b64_tr_b16 v[156:157], v147 offset:11776
	v_add_f32_e32 v169, v169, v90
	v_exp_f32_e32 v93, v93
	v_add_f32_e32 v169, v169, v91
	v_cvt_pk_bf16_f32 v181, v90, v91
	s_waitcnt lgkmcnt(6)
	v_mfma_f32_32x32x16_bf16 v[16:31], v[158:161], v[188:191], v[16:31]
	ds_read_b64_tr_b16 v[158:159], v147 offset:9280
	ds_read_b64_tr_b16 v[160:161], v147 offset:11840
	v_add3_u32 v174, s57, v213, v138
	v_add3_u32 v175, s57, v141, v221
	v_add3_u32 v210, s58, v213, v138
	v_add3_u32 v211, s58, v141, v221
	v_exp_f32_e32 v94, v94
	v_add_f32_e32 v169, v169, v92
	v_exp_f32_e32 v95, v95
	s_waitcnt lgkmcnt(6)
	v_mfma_f32_32x32x16_bf16 v[48:63], v[162:165], v[188:191], v[48:63]
	ds_read_b64_tr_b16 v[162:163], v147 offset:9344
	ds_read_b64_tr_b16 v[164:165], v147 offset:11904
	s_mov_b32 s2, s56
	s_mov_b32 s56, s57
	s_mov_b32 s57, s58
	s_mov_b32 s58, s2
	s_add_i32 s59, s59, 1
	v_add3_u32 v248, s58, v212, v139
	v_add3_u32 v249, s58, v219, v140
	v_add3_u32 v133, s58, v220, v140
	v_add_f32_e32 v169, v169, v93
	v_cvt_pk_bf16_f32 v182, v92, v93
	v_add_f32_e32 v169, v169, v94
	v_add_f32_e32 v169, v169, v95
	v_cvt_pk_bf16_f32 v183, v94, v95
	s_waitcnt lgkmcnt(6)
	v_mfma_f32_32x32x16_bf16 v[64:79], v[230:233], v[188:191], v[64:79]
	ds_read_b64_tr_b16 v[230:231], v147 offset:9408
	ds_read_b64_tr_b16 v[232:233], v147 offset:11968
	s_waitcnt lgkmcnt(10)
	s_barrier
	v_mfma_f32_32x32x16_bf16 v[80:95], v[198:201], v[96:99], v[32:47]
	ds_read_b128 v[198:201], v174 offset:4608
	v_exp_f32_e32 v112, v112
	v_exp_f32_e32 v113, v113
	v_exp_f32_e32 v114, v114
	v_mfma_f32_32x32x16_bf16 v[80:95], v[202:205], v[100:103], v[80:95]
	ds_read_b128 v[202:205], v174 offset:4640
	v_add_f32_e32 v169, v169, v112
	v_exp_f32_e32 v115, v115
	v_add_f32_e32 v169, v169, v113
	v_cvt_pk_bf16_f32 v184, v112, v113
	v_mfma_f32_32x32x16_bf16 v[80:95], v[206:209], v[104:107], v[80:95]
	ds_read_b128 v[206:209], v174 offset:4672
	v_exp_f32_e32 v116, v116
	v_add_f32_e32 v169, v169, v114
	v_exp_f32_e32 v117, v117
	v_mfma_f32_32x32x16_bf16 v[80:95], v[150:153], v[108:111], v[80:95]
	ds_read_b128 v[150:153], v174 offset:4704
	v_add_f32_e32 v169, v169, v115
	v_cvt_pk_bf16_f32 v185, v114, v115
	v_exp_f32_e32 v118, v118
	v_add_f32_e32 v169, v169, v116
	s_waitcnt lgkmcnt(10)
	v_mfma_f32_32x32x16_bf16 v[0:15], v[154:157], v[176:179], v[0:15]
	ds_read_b64_tr_b16 v[154:155], v175 offset:14336
	ds_read_b64_tr_b16 v[156:157], v175 offset:16896
	s_waitcnt vmcnt(0)
	ds_write_b128 v248, v[234:237]
	v_exp_f32_e32 v119, v119
	v_add_f32_e32 v169, v169, v117
	v_cvt_pk_bf16_f32 v186, v116, v117
	v_exp_f32_e32 v120, v120
	s_waitcnt lgkmcnt(11)
	v_mfma_f32_32x32x16_bf16 v[16:31], v[158:161], v[176:179], v[16:31]
	ds_read_b64_tr_b16 v[158:159], v175 offset:14400
	ds_read_b64_tr_b16 v[160:161], v175 offset:16960
	ds_write_b128 v249, v[128:131] offset:9216
	v_add_f32_e32 v169, v169, v118
	v_exp_f32_e32 v121, v121
	v_add_f32_e32 v169, v169, v119
	s_waitcnt lgkmcnt(12)
	v_mfma_f32_32x32x16_bf16 v[48:63], v[162:165], v[176:179], v[48:63]
	ds_read_b64_tr_b16 v[162:163], v175 offset:14464
	ds_read_b64_tr_b16 v[164:165], v175 offset:17024
	ds_write_b128 v133, v[170:173] offset:9216
	v_cvt_pk_bf16_f32 v187, v118, v119
	v_exp_f32_e32 v122, v122
	v_add_f32_e32 v169, v169, v120
	v_exp_f32_e32 v123, v123
	s_waitcnt lgkmcnt(13)
	v_mfma_f32_32x32x16_bf16 v[64:79], v[230:233], v[176:179], v[64:79]
	ds_read_b64_tr_b16 v[230:231], v175 offset:14528
	ds_read_b64_tr_b16 v[232:233], v175 offset:17088
	s_add_i32 s71, s25, -1
	s_add_i32 s70, s59, 3
	s_min_u32 s70, s70, s71
	s_cmp_lt_u32 s70, 4
	s_cselect_b32 s2, s65, s32
	s_lshl_b32 s3, s70, 6
	s_add_i32 s2, s2, s3
	s_lshl_b32 s2, s2, 10
	s_add_u32 s60, s66, s2
	s_addc_u32 s61, s67, 0
	s_add_i32 s70, s59, 2
	s_min_u32 s70, s70, s71
	s_cmp_lt_u32 s70, 4
	s_cselect_b32 s2, s65, s32
	s_lshl_b32 s3, s70, 6
	s_add_i32 s2, s2, s3
	s_lshl_b32 s2, s2, 10
	s_add_u32 s62, s68, s2
	s_addc_u32 s63, s69, 0
	v_add_f32_e32 v169, v169, v121
	v_cvt_pk_bf16_f32 v188, v120, v121
	v_exp_f32_e32 v124, v124
	s_waitcnt lgkmcnt(9)
	v_mfma_f32_32x32x16_bf16 v[0:15], v[154:157], v[180:183], v[0:15]
	ds_read_b64_tr_b16 v[154:155], v175 offset:19456
	ds_read_b64_tr_b16 v[156:157], v175 offset:22016
	global_load_dwordx4 v[234:237], v166, s[60:61]
	global_load_dwordx4 v[128:131], v167, s[62:63]
	global_load_dwordx4 v[170:173], v132, s[62:63]
	v_add_f32_e32 v169, v169, v122
	v_exp_f32_e32 v125, v125
	v_add_f32_e32 v169, v169, v123
	v_cvt_pk_bf16_f32 v189, v122, v123
	s_waitcnt lgkmcnt(8)
	v_mfma_f32_32x32x16_bf16 v[16:31], v[158:161], v[180:183], v[16:31]
	ds_read_b64_tr_b16 v[158:159], v175 offset:19520
	ds_read_b64_tr_b16 v[160:161], v175 offset:22080
	v_exp_f32_e32 v126, v126
	v_add_f32_e32 v169, v169, v124
	v_exp_f32_e32 v127, v127
	s_waitcnt lgkmcnt(7)
	v_mfma_f32_32x32x16_bf16 v[48:63], v[162:165], v[180:183], v[48:63]
	ds_read_b64_tr_b16 v[162:163], v175 offset:19584
	ds_read_b64_tr_b16 v[164:165], v175 offset:22144
	v_add_f32_e32 v169, v169, v125
	v_cvt_pk_bf16_f32 v190, v124, v125
	v_add_f32_e32 v169, v169, v126
	v_add_f32_e32 v169, v169, v127
	v_cvt_pk_bf16_f32 v191, v126, v127
	s_waitcnt lgkmcnt(6)
; template <int DV>
; __device__ __forceinline__ void attn_pass(const int tid, unsigned char* smem, const bf16_t* Q0, int qpitch, const bf16_t* Kb, int kpitch, const bf16_t* Vb, int vpitch,
;                                           int b, int ntiles, float kmax, f32x16 (&o)[DV / 32], float& linv) {
;     ...
;     for (int kt = 0; kt < ntiles; ++kt) {
;         if (kt + 1 < ntiles) gload(kt + 1);
;         const unsigned char* Ks = smem + (kt & 1) * BUF; const unsigned char* Vs = Ks + KBYTES;
;         const unsigned char* kp = Ks + r32 * KP + hi * 16;
;         bf16x8 pf[2][2];
; #pragma unroll
;         for (int kb = 0; kb < 2; ++kb) {
;             f32x16 s;
; #pragma unroll
;             for (int r = 0; r < 16; ++r) s[r] = nshift;
; #pragma unroll
;             for (int ds = 0; ds < 4; ++ds) {
;                 const bf16x8 kf = *(const bf16x8*)(kp + kb * 32 * KP + ds * 32);
;                 s = __builtin_amdgcn_mfma_f32_32x32x16_bf16(kf, qf[ds], s, 0, 0, 0);
;             }
;             float ls = 0.f;
; #pragma unroll
;             for (int r = 0; r < 16; ++r) { s[r] = __builtin_amdgcn_exp2f(s[r]); ls += s[r]; }
;             lsum += ls;
; #pragma unroll
;             for (int j = 0; j < 2; ++j) {
;                 u32x4 w0;
;                 w0.x = cvt_pk_bf16(s[8 * j + 0], s[8 * j + 1]); w0.y = cvt_pk_bf16(s[8 * j + 2], s[8 * j + 3]); w0.z = cvt_pk_bf16(s[8 * j + 4], s[8 * j + 5]); w0.w = cvt_pk_bf16(s[8 * j + 6], s[8 * j + 7]);
;                 pf[kb][j] = __builtin_bit_cast(bf16x8, w0);
;             }
;         }
;         const unsigned char* vp = Vs + (4 * hi + q4) * VP + (16 * nhalf + 4 * p4) * 2;
; #pragma unroll
;         for (int d0 = 0; d0 < DV / 32; ++d0) {
; #pragma unroll
;             for (int kb = 0; kb < 2; ++kb)
; #pragma unroll
;                 for (int j = 0; j < 2; ++j) {
;                     const unsigned char* a = vp + (32 * kb + 16 * j) * VP + d0 * 64;
;                     const s16x4 lo = ld_tr(a), h4 = ld_tr(a + 8 * VP);
;                     const bf16x8 vf = (bf16x8){lo[0], lo[1], lo[2], lo[3], h4[0], h4[1], h4[2], h4[3]};
;                     o[d0] = __builtin_amdgcn_mfma_f32_32x32x16_bf16(vf, pf[kb][j], o[d0], 0, 0, 0);
;                 }
;             if (d0 & 1) __builtin_amdgcn_sched_barrier(0);
;         }
;         if (kt + 1 < ntiles) lwrite((kt + 1) & 1);
;         __syncthreads();
;     }
	v_mfma_f32_32x32x16_bf16 v[64:79], v[230:233], v[180:183], v[64:79]
	ds_read_b64_tr_b16 v[230:231], v175 offset:19648
	ds_read_b64_tr_b16 v[232:233], v175 offset:22208
	v_mfma_f32_32x32x16_bf16 v[112:127], v[198:201], v[96:99], v[32:47]
	ds_read_b128 v[198:201], v210 offset:0
	v_exp_f32_e32 v80, v80
	v_exp_f32_e32 v81, v81
	v_exp_f32_e32 v82, v82
	v_mfma_f32_32x32x16_bf16 v[112:127], v[202:205], v[100:103], v[112:127]
	ds_read_b128 v[202:205], v210 offset:32
	v_add_f32_e32 v169, v169, v80
	v_exp_f32_e32 v83, v83
	v_add_f32_e32 v169, v169, v81
	v_cvt_pk_bf16_f32 v176, v80, v81
	v_mfma_f32_32x32x16_bf16 v[112:127], v[206:209], v[104:107], v[112:127]
	ds_read_b128 v[206:209], v210 offset:64
	v_exp_f32_e32 v84, v84
	v_add_f32_e32 v169, v169, v82
	v_exp_f32_e32 v85, v85
	v_mfma_f32_32x32x16_bf16 v[112:127], v[150:153], v[108:111], v[112:127]
	ds_read_b128 v[150:153], v210 offset:96
	v_add_f32_e32 v169, v169, v83
	v_cvt_pk_bf16_f32 v177, v82, v83
	v_exp_f32_e32 v86, v86
	v_add_f32_e32 v169, v169, v84
	s_waitcnt lgkmcnt(10)
	v_mfma_f32_32x32x16_bf16 v[0:15], v[154:157], v[184:187], v[0:15]
	ds_read_b64_tr_b16 v[154:155], v175 offset:24576
	ds_read_b64_tr_b16 v[156:157], v175 offset:27136
	v_exp_f32_e32 v87, v87
	v_add_f32_e32 v169, v169, v85
	v_cvt_pk_bf16_f32 v178, v84, v85
	v_exp_f32_e32 v88, v88
	s_waitcnt lgkmcnt(10)
	v_mfma_f32_32x32x16_bf16 v[16:31], v[158:161], v[184:187], v[16:31]
	ds_read_b64_tr_b16 v[158:159], v175 offset:24640
	ds_read_b64_tr_b16 v[160:161], v175 offset:27200
	v_add_f32_e32 v169, v169, v86
	v_exp_f32_e32 v89, v89
	v_add_f32_e32 v169, v169, v87
	s_waitcnt lgkmcnt(10)
	v_mfma_f32_32x32x16_bf16 v[48:63], v[162:165], v[184:187], v[48:63]
	ds_read_b64_tr_b16 v[162:163], v175 offset:24704
	ds_read_b64_tr_b16 v[164:165], v175 offset:27264
	v_cvt_pk_bf16_f32 v179, v86, v87
	v_exp_f32_e32 v90, v90
	v_add_f32_e32 v169, v169, v88
	v_exp_f32_e32 v91, v91
	s_waitcnt lgkmcnt(10)
	v_mfma_f32_32x32x16_bf16 v[64:79], v[230:233], v[184:187], v[64:79]
	ds_read_b64_tr_b16 v[230:231], v175 offset:24768
	ds_read_b64_tr_b16 v[232:233], v175 offset:27328
	v_add_f32_e32 v169, v169, v89
	v_cvt_pk_bf16_f32 v180, v88, v89
	v_exp_f32_e32 v92, v92
	s_waitcnt lgkmcnt(6)
	v_mfma_f32_32x32x16_bf16 v[0:15], v[154:157], v[188:191], v[0:15]
	ds_read_b64_tr_b16 v[154:155], v211 offset:9216
	ds_read_b64_tr_b16 v[156:157], v211 offset:11776
	v_add_f32_e32 v169, v169, v90
	v_exp_f32_e32 v93, v93
	v_add_f32_e32 v169, v169, v91
	v_cvt_pk_bf16_f32 v181, v90, v91
	s_waitcnt lgkmcnt(6)
	v_mfma_f32_32x32x16_bf16 v[16:31], v[158:161], v[188:191], v[16:31]
	ds_read_b64_tr_b16 v[158:159], v211 offset:9280
	ds_read_b64_tr_b16 v[160:161], v211 offset:11840
	v_add3_u32 v142, s57, v213, v138
	v_add3_u32 v143, s57, v141, v221
	v_add3_u32 v146, s58, v213, v138
	v_add3_u32 v147, s58, v141, v221
	v_exp_f32_e32 v94, v94
	v_add_f32_e32 v169, v169, v92
	v_exp_f32_e32 v95, v95
	s_waitcnt lgkmcnt(6)
	v_mfma_f32_32x32x16_bf16 v[48:63], v[162:165], v[188:191], v[48:63]
	ds_read_b64_tr_b16 v[162:163], v211 offset:9344
	ds_read_b64_tr_b16 v[164:165], v211 offset:11904
	s_mov_b32 s2, s56
	s_mov_b32 s56, s57
	s_mov_b32 s57, s58
	s_mov_b32 s58, s2
	s_add_i32 s59, s59, 1
	v_add3_u32 v248, s58, v212, v139
	v_add3_u32 v249, s58, v219, v140
	v_add3_u32 v133, s58, v220, v140
	v_add_f32_e32 v169, v169, v93
	v_cvt_pk_bf16_f32 v182, v92, v93
	v_add_f32_e32 v169, v169, v94
	v_add_f32_e32 v169, v169, v95
	v_cvt_pk_bf16_f32 v183, v94, v95
	s_waitcnt lgkmcnt(6)
	v_mfma_f32_32x32x16_bf16 v[64:79], v[230:233], v[188:191], v[64:79]
	ds_read_b64_tr_b16 v[230:231], v211 offset:9408
	ds_read_b64_tr_b16 v[232:233], v211 offset:11968
	s_add_i32 s71, s25, -1
	s_cmp_lt_u32 s59, s71
	s_waitcnt lgkmcnt(10)
	s_barrier
	s_cbranch_scc1 .Lcattn_loop
	v_mfma_f32_32x32x16_bf16 v[80:95], v[198:201], v[96:99], v[32:47]
	ds_read_b128 v[198:201], v142 offset:4608
	v_exp_f32_e32 v112, v112
	v_exp_f32_e32 v113, v113
	v_exp_f32_e32 v114, v114
	v_mfma_f32_32x32x16_bf16 v[80:95], v[202:205], v[100:103], v[80:95]
	ds_read_b128 v[202:205], v142 offset:4640
	v_add_f32_e32 v169, v169, v112
	v_exp_f32_e32 v115, v115
	v_add_f32_e32 v169, v169, v113
	v_cvt_pk_bf16_f32 v184, v112, v113
	v_mfma_f32_32x32x16_bf16 v[80:95], v[206:209], v[104:107], v[80:95]
	ds_read_b128 v[206:209], v142 offset:4672
	v_exp_f32_e32 v116, v116
	v_add_f32_e32 v169, v169, v114
	v_exp_f32_e32 v117, v117
	v_mfma_f32_32x32x16_bf16 v[80:95], v[150:153], v[108:111], v[80:95]
	ds_read_b128 v[150:153], v142 offset:4704
	v_add_f32_e32 v169, v169, v115
	v_cvt_pk_bf16_f32 v185, v114, v115
	v_exp_f32_e32 v118, v118
	v_add_f32_e32 v169, v169, v116
	s_waitcnt lgkmcnt(10)
	v_mfma_f32_32x32x16_bf16 v[0:15], v[154:157], v[176:179], v[0:15]
	ds_read_b64_tr_b16 v[154:155], v143 offset:14336
	ds_read_b64_tr_b16 v[156:157], v143 offset:16896
	v_exp_f32_e32 v119, v119
	v_add_f32_e32 v169, v169, v117
	v_cvt_pk_bf16_f32 v186, v116, v117
	v_exp_f32_e32 v120, v120
	s_waitcnt lgkmcnt(10)
	v_mfma_f32_32x32x16_bf16 v[16:31], v[158:161], v[176:179], v[16:31]
	ds_read_b64_tr_b16 v[158:159], v143 offset:14400
	ds_read_b64_tr_b16 v[160:161], v143 offset:16960
	v_add_f32_e32 v169, v169, v118
	v_exp_f32_e32 v121, v121
	v_add_f32_e32 v169, v169, v119
	s_waitcnt lgkmcnt(10)
	v_mfma_f32_32x32x16_bf16 v[48:63], v[162:165], v[176:179], v[48:63]
	ds_read_b64_tr_b16 v[162:163], v143 offset:14464
	ds_read_b64_tr_b16 v[164:165], v143 offset:17024
	v_cvt_pk_bf16_f32 v187, v118, v119
	v_exp_f32_e32 v122, v122
	v_add_f32_e32 v169, v169, v120
	v_exp_f32_e32 v123, v123
	s_waitcnt lgkmcnt(10)
; template <int DV>
; __device__ __forceinline__ void attn_pass(const int tid, unsigned char* smem, const bf16_t* Q0, int qpitch, const bf16_t* Kb, int kpitch, const bf16_t* Vb, int vpitch,
;                                           int b, int ntiles, float kmax, f32x16 (&o)[DV / 32], float& linv) {
;     ...
;     for (int kt = 0; kt < ntiles; ++kt) {
;         if (kt + 1 < ntiles) gload(kt + 1);
;         const unsigned char* Ks = smem + (kt & 1) * BUF; const unsigned char* Vs = Ks + KBYTES;
;         const unsigned char* kp = Ks + r32 * KP + hi * 16;
;         bf16x8 pf[2][2];
; #pragma unroll
;         for (int kb = 0; kb < 2; ++kb) {
;             f32x16 s;
; #pragma unroll
;             for (int r = 0; r < 16; ++r) s[r] = nshift;
; #pragma unroll
;             for (int ds = 0; ds < 4; ++ds) {
;                 const bf16x8 kf = *(const bf16x8*)(kp + kb * 32 * KP + ds * 32);
;                 s = __builtin_amdgcn_mfma_f32_32x32x16_bf16(kf, qf[ds], s, 0, 0, 0);
;             }
;             float ls = 0.f;
; #pragma unroll
;             for (int r = 0; r < 16; ++r) { s[r] = __builtin_amdgcn_exp2f(s[r]); ls += s[r]; }
;             lsum += ls;
; #pragma unroll
;             for (int j = 0; j < 2; ++j) {
;                 u32x4 w0;
;                 w0.x = cvt_pk_bf16(s[8 * j + 0], s[8 * j + 1]); w0.y = cvt_pk_bf16(s[8 * j + 2], s[8 * j + 3]); w0.z = cvt_pk_bf16(s[8 * j + 4], s[8 * j + 5]); w0.w = cvt_pk_bf16(s[8 * j + 6], s[8 * j + 7]);
;                 pf[kb][j] = __builtin_bit_cast(bf16x8, w0);
;             }
;         }
;         const unsigned char* vp = Vs + (4 * hi + q4) * VP + (16 * nhalf + 4 * p4) * 2;
; #pragma unroll
;         for (int d0 = 0; d0 < DV / 32; ++d0) {
; #pragma unroll
;             for (int kb = 0; kb < 2; ++kb)
; #pragma unroll
;                 for (int j = 0; j < 2; ++j) {
;                     const unsigned char* a = vp + (32 * kb + 16 * j) * VP + d0 * 64;
;                     const s16x4 lo = ld_tr(a), h4 = ld_tr(a + 8 * VP);
;                     const bf16x8 vf = (bf16x8){lo[0], lo[1], lo[2], lo[3], h4[0], h4[1], h4[2], h4[3]};
;                     o[d0] = __builtin_amdgcn_mfma_f32_32x32x16_bf16(vf, pf[kb][j], o[d0], 0, 0, 0);
;                 }
;             if (d0 & 1) __builtin_amdgcn_sched_barrier(0);
;         }
;         if (kt + 1 < ntiles) lwrite((kt + 1) & 1);
;         __syncthreads();
;     }
	v_mfma_f32_32x32x16_bf16 v[64:79], v[230:233], v[176:179], v[64:79]
	ds_read_b64_tr_b16 v[230:231], v143 offset:14528
	ds_read_b64_tr_b16 v[232:233], v143 offset:17088
	v_add_f32_e32 v169, v169, v121
	v_cvt_pk_bf16_f32 v188, v120, v121
	v_exp_f32_e32 v124, v124
	s_waitcnt lgkmcnt(6)
	v_mfma_f32_32x32x16_bf16 v[0:15], v[154:157], v[180:183], v[0:15]
	ds_read_b64_tr_b16 v[154:155], v143 offset:19456
	ds_read_b64_tr_b16 v[156:157], v143 offset:22016
	v_add_f32_e32 v169, v169, v122
	v_exp_f32_e32 v125, v125
	v_add_f32_e32 v169, v169, v123
	v_cvt_pk_bf16_f32 v189, v122, v123
	s_waitcnt lgkmcnt(6)
	v_mfma_f32_32x32x16_bf16 v[16:31], v[158:161], v[180:183], v[16:31]
	ds_read_b64_tr_b16 v[158:159], v143 offset:19520
	ds_read_b64_tr_b16 v[160:161], v143 offset:22080
	v_exp_f32_e32 v126, v126
	v_add_f32_e32 v169, v169, v124
	v_exp_f32_e32 v127, v127
	s_waitcnt lgkmcnt(6)
	v_mfma_f32_32x32x16_bf16 v[48:63], v[162:165], v[180:183], v[48:63]
	ds_read_b64_tr_b16 v[162:163], v143 offset:19584
	ds_read_b64_tr_b16 v[164:165], v143 offset:22144
	v_add_f32_e32 v169, v169, v125
	v_cvt_pk_bf16_f32 v190, v124, v125
	v_add_f32_e32 v169, v169, v126
	v_add_f32_e32 v169, v169, v127
	v_cvt_pk_bf16_f32 v191, v126, v127
	s_waitcnt lgkmcnt(6)
	v_mfma_f32_32x32x16_bf16 v[64:79], v[230:233], v[180:183], v[64:79]
	ds_read_b64_tr_b16 v[230:231], v143 offset:19648
	ds_read_b64_tr_b16 v[232:233], v143 offset:22208
	v_mfma_f32_32x32x16_bf16 v[112:127], v[198:201], v[96:99], v[32:47]
	v_exp_f32_e32 v80, v80
	v_exp_f32_e32 v81, v81
	v_exp_f32_e32 v82, v82
	v_mfma_f32_32x32x16_bf16 v[112:127], v[202:205], v[100:103], v[112:127]
	v_add_f32_e32 v169, v169, v80
	v_exp_f32_e32 v83, v83
	v_add_f32_e32 v169, v169, v81
	v_cvt_pk_bf16_f32 v176, v80, v81
	v_mfma_f32_32x32x16_bf16 v[112:127], v[206:209], v[104:107], v[112:127]
	v_exp_f32_e32 v84, v84
	v_add_f32_e32 v169, v169, v82
	v_exp_f32_e32 v85, v85
	v_mfma_f32_32x32x16_bf16 v[112:127], v[150:153], v[108:111], v[112:127]
	v_add_f32_e32 v169, v169, v83
	v_cvt_pk_bf16_f32 v177, v82, v83
	v_exp_f32_e32 v86, v86
	v_add_f32_e32 v169, v169, v84
	s_waitcnt lgkmcnt(6)
	v_mfma_f32_32x32x16_bf16 v[0:15], v[154:157], v[184:187], v[0:15]
	ds_read_b64_tr_b16 v[154:155], v143 offset:24576
	ds_read_b64_tr_b16 v[156:157], v143 offset:27136
	v_exp_f32_e32 v87, v87
	v_add_f32_e32 v169, v169, v85
	v_cvt_pk_bf16_f32 v178, v84, v85
	v_exp_f32_e32 v88, v88
	s_waitcnt lgkmcnt(6)
	v_mfma_f32_32x32x16_bf16 v[16:31], v[158:161], v[184:187], v[16:31]
	ds_read_b64_tr_b16 v[158:159], v143 offset:24640
	ds_read_b64_tr_b16 v[160:161], v143 offset:27200
	v_add_f32_e32 v169, v169, v86
	v_exp_f32_e32 v89, v89
	v_add_f32_e32 v169, v169, v87
	s_waitcnt lgkmcnt(6)
	v_mfma_f32_32x32x16_bf16 v[48:63], v[162:165], v[184:187], v[48:63]
	ds_read_b64_tr_b16 v[162:163], v143 offset:24704
	ds_read_b64_tr_b16 v[164:165], v143 offset:27264
	v_cvt_pk_bf16_f32 v179, v86, v87
	v_exp_f32_e32 v90, v90
	v_add_f32_e32 v169, v169, v88
	v_exp_f32_e32 v91, v91
	s_waitcnt lgkmcnt(6)
	v_mfma_f32_32x32x16_bf16 v[64:79], v[230:233], v[184:187], v[64:79]
	ds_read_b64_tr_b16 v[230:231], v143 offset:24768
	ds_read_b64_tr_b16 v[232:233], v143 offset:27328
	v_add_f32_e32 v169, v169, v89
	v_cvt_pk_bf16_f32 v180, v88, v89
	v_exp_f32_e32 v92, v92
	s_waitcnt lgkmcnt(6)
	v_mfma_f32_32x32x16_bf16 v[0:15], v[154:157], v[188:191], v[0:15]
	ds_read_b64_tr_b16 v[154:155], v147 offset:9216
	ds_read_b64_tr_b16 v[156:157], v147 offset:11776
	v_add_f32_e32 v169, v169, v90
	v_exp_f32_e32 v93, v93
	v_add_f32_e32 v169, v169, v91
	v_cvt_pk_bf16_f32 v181, v90, v91
	s_waitcnt lgkmcnt(6)
	v_mfma_f32_32x32x16_bf16 v[16:31], v[158:161], v[188:191], v[16:31]
	ds_read_b64_tr_b16 v[158:159], v147 offset:9280
	ds_read_b64_tr_b16 v[160:161], v147 offset:11840
	v_add3_u32 v174, s57, v213, v138
	v_add3_u32 v175, s57, v141, v221
	v_add3_u32 v210, s58, v213, v138
	v_add3_u32 v211, s58, v141, v221
	v_exp_f32_e32 v94, v94
	v_add_f32_e32 v169, v169, v92
	v_exp_f32_e32 v95, v95
	s_waitcnt lgkmcnt(6)
	v_mfma_f32_32x32x16_bf16 v[48:63], v[162:165], v[188:191], v[48:63]
	ds_read_b64_tr_b16 v[162:163], v147 offset:9344
	ds_read_b64_tr_b16 v[164:165], v147 offset:11904
	s_mov_b32 s2, s56
	s_mov_b32 s56, s57
	s_mov_b32 s57, s58
	s_mov_b32 s58, s2
	s_add_i32 s59, s59, 1
	v_add3_u32 v248, s58, v212, v139
	v_add3_u32 v249, s58, v219, v140
	v_add3_u32 v133, s58, v220, v140
	v_add_f32_e32 v169, v169, v93
	v_cvt_pk_bf16_f32 v182, v92, v93
	v_add_f32_e32 v169, v169, v94
	v_add_f32_e32 v169, v169, v95
	v_cvt_pk_bf16_f32 v183, v94, v95
	s_waitcnt lgkmcnt(6)
	v_mfma_f32_32x32x16_bf16 v[64:79], v[230:233], v[188:191], v[64:79]
	ds_read_b64_tr_b16 v[230:231], v147 offset:9408
	ds_read_b64_tr_b16 v[232:233], v147 offset:11968
	s_waitcnt lgkmcnt(0)
	s_barrier
; __device__ __forceinline__ s16x4 ld_tr(const unsigned char* p) { return __builtin_bit_cast(s16x4, __builtin_amdgcn_ds_read_tr16_b64_v4i16((LAS s16x4*)p)); }
; template <int DV>
; __device__ __forceinline__ void attn_pass(const int tid, unsigned char* smem, const bf16_t* Q0, int qpitch, const bf16_t* Kb, int kpitch, const bf16_t* Vb, int vpitch,
;                                           int b, int ntiles, float kmax, f32x16 (&o)[DV / 32], float& linv) {
;     ...
;         const unsigned char* vp = Vs + (4 * hi + q4) * VP + (16 * nhalf + 4 * p4) * 2;
; #pragma unroll
;         for (int d0 = 0; d0 < DV / 32; ++d0) {
; #pragma unroll
;             for (int kb = 0; kb < 2; ++kb)
; #pragma unroll
;                 for (int j = 0; j < 2; ++j) {
;                     const unsigned char* a = vp + (32 * kb + 16 * j) * VP + d0 * 64;
;                     const s16x4 lo = ld_tr(a), h4 = ld_tr(a + 8 * VP);
;                     const bf16x8 vf = (bf16x8){lo[0], lo[1], lo[2], lo[3], h4[0], h4[1], h4[2], h4[3]};
;                     o[d0] = __builtin_amdgcn_mfma_f32_32x32x16_bf16(vf, pf[kb][j], o[d0], 0, 0, 0);
;                 }
;             if (d0 & 1) __builtin_amdgcn_sched_barrier(0);
;         }
;         if (kt + 1 < ntiles) lwrite((kt + 1) & 1);
;         __syncthreads();
;     }
	v_mfma_f32_32x32x16_bf16 v[0:15], v[154:157], v[176:179], v[0:15]
	ds_read_b64_tr_b16 v[154:155], v175 offset:14336
	ds_read_b64_tr_b16 v[156:157], v175 offset:16896
	v_exp_f32_e32 v112, v112
	v_exp_f32_e32 v113, v113
	v_exp_f32_e32 v114, v114
	v_add_f32_e32 v169, v169, v112
	v_exp_f32_e32 v115, v115
	v_mfma_f32_32x32x16_bf16 v[16:31], v[158:161], v[176:179], v[16:31]
	ds_read_b64_tr_b16 v[158:159], v175 offset:14400
	ds_read_b64_tr_b16 v[160:161], v175 offset:16960
	v_add_f32_e32 v169, v169, v113
	v_cvt_pk_bf16_f32 v184, v112, v113
	v_exp_f32_e32 v116, v116
	v_add_f32_e32 v169, v169, v114
	v_exp_f32_e32 v117, v117
	v_mfma_f32_32x32x16_bf16 v[48:63], v[162:165], v[176:179], v[48:63]
	ds_read_b64_tr_b16 v[162:163], v175 offset:14464
	ds_read_b64_tr_b16 v[164:165], v175 offset:17024
	v_add_f32_e32 v169, v169, v115
	v_cvt_pk_bf16_f32 v185, v114, v115
	v_exp_f32_e32 v118, v118
	v_add_f32_e32 v169, v169, v116
	v_exp_f32_e32 v119, v119
	v_add_f32_e32 v169, v169, v117
	v_mfma_f32_32x32x16_bf16 v[64:79], v[230:233], v[176:179], v[64:79]
	ds_read_b64_tr_b16 v[230:231], v175 offset:14528
	ds_read_b64_tr_b16 v[232:233], v175 offset:17088
	v_cvt_pk_bf16_f32 v186, v116, v117
	v_exp_f32_e32 v120, v120
	v_add_f32_e32 v169, v169, v118
	v_exp_f32_e32 v121, v121
	v_add_f32_e32 v169, v169, v119
	v_cvt_pk_bf16_f32 v187, v118, v119
	s_waitcnt lgkmcnt(6)
	v_mfma_f32_32x32x16_bf16 v[0:15], v[154:157], v[180:183], v[0:15]
	ds_read_b64_tr_b16 v[154:155], v175 offset:19456
	ds_read_b64_tr_b16 v[156:157], v175 offset:22016
	v_exp_f32_e32 v122, v122
	v_add_f32_e32 v169, v169, v120
	v_exp_f32_e32 v123, v123
	v_add_f32_e32 v169, v169, v121
	v_cvt_pk_bf16_f32 v188, v120, v121
	v_exp_f32_e32 v124, v124
	s_waitcnt lgkmcnt(6)
	v_mfma_f32_32x32x16_bf16 v[16:31], v[158:161], v[180:183], v[16:31]
	ds_read_b64_tr_b16 v[158:159], v175 offset:19520
	ds_read_b64_tr_b16 v[160:161], v175 offset:22080
	v_add_f32_e32 v169, v169, v122
	v_exp_f32_e32 v125, v125
	v_add_f32_e32 v169, v169, v123
	v_cvt_pk_bf16_f32 v189, v122, v123
	v_exp_f32_e32 v126, v126
	s_waitcnt lgkmcnt(6)
	v_mfma_f32_32x32x16_bf16 v[48:63], v[162:165], v[180:183], v[48:63]
	ds_read_b64_tr_b16 v[162:163], v175 offset:19584
	ds_read_b64_tr_b16 v[164:165], v175 offset:22144
	v_add_f32_e32 v169, v169, v124
	v_exp_f32_e32 v127, v127
	v_add_f32_e32 v169, v169, v125
	v_cvt_pk_bf16_f32 v190, v124, v125
	v_add_f32_e32 v169, v169, v126
	v_add_f32_e32 v169, v169, v127
	v_cvt_pk_bf16_f32 v191, v126, v127
	s_waitcnt lgkmcnt(6)
	v_mfma_f32_32x32x16_bf16 v[64:79], v[230:233], v[180:183], v[64:79]
	ds_read_b64_tr_b16 v[230:231], v175 offset:19648
	ds_read_b64_tr_b16 v[232:233], v175 offset:22208
	s_waitcnt lgkmcnt(6)
	v_mfma_f32_32x32x16_bf16 v[0:15], v[154:157], v[184:187], v[0:15]
	ds_read_b64_tr_b16 v[154:155], v175 offset:24576
	ds_read_b64_tr_b16 v[156:157], v175 offset:27136
	s_waitcnt lgkmcnt(6)
	v_mfma_f32_32x32x16_bf16 v[16:31], v[158:161], v[184:187], v[16:31]
	ds_read_b64_tr_b16 v[158:159], v175 offset:24640
	ds_read_b64_tr_b16 v[160:161], v175 offset:27200
	s_waitcnt lgkmcnt(6)
	v_mfma_f32_32x32x16_bf16 v[48:63], v[162:165], v[184:187], v[48:63]
	ds_read_b64_tr_b16 v[162:163], v175 offset:24704
	ds_read_b64_tr_b16 v[164:165], v175 offset:27264
	s_waitcnt lgkmcnt(6)
	v_mfma_f32_32x32x16_bf16 v[64:79], v[230:233], v[184:187], v[64:79]
	ds_read_b64_tr_b16 v[230:231], v175 offset:24768
	ds_read_b64_tr_b16 v[232:233], v175 offset:27328
	s_waitcnt lgkmcnt(6)
	v_mfma_f32_32x32x16_bf16 v[0:15], v[154:157], v[188:191], v[0:15]
	s_waitcnt lgkmcnt(4)
	v_mfma_f32_32x32x16_bf16 v[16:31], v[158:161], v[188:191], v[16:31]
	s_waitcnt lgkmcnt(2)
	v_mfma_f32_32x32x16_bf16 v[48:63], v[162:165], v[188:191], v[48:63]
	s_waitcnt lgkmcnt(0)
	v_mfma_f32_32x32x16_bf16 v[64:79], v[230:233], v[188:191], v[64:79]
	s_waitcnt lgkmcnt(0)
	s_barrier
	s_waitcnt vmcnt(0)
